# seam barriers: L1 invalidate issued and waited by wave 1 behind the seam's first s_barrier (leader's memory queue carries no invalidate)
# speedup vs baseline: 1.0089x; 1.0013x over previous
.LBB0_114:
	s_cmp_gt_i32 s89, 1
	s_cselect_b64 s[6:7], -1, 0
	s_and_b64 s[8:9], s[24:25], s[6:7]
	s_andn2_b64 vcc, exec, s[8:9]
	s_cbranch_vccnz .LBB0_168
	s_waitcnt vmcnt(0)
	s_waitcnt lgkmcnt(0)
	s_barrier
	v_readfirstlane_b32 s98, v208
	s_cmp_eq_u32 s98, 64
	s_cbranch_scc0 .Lseam_inv_skip_0
	buffer_inv sc1
	s_waitcnt vmcnt(0)
.Lseam_inv_skip_0:
	s_and_saveexec_b64 s[8:9], s[26:27]
	s_cbranch_execz .LBB0_167
	s_add_i32 s10, 0, 0x22020
	v_mov_b32_e32 v0, s10
	s_waitcnt vmcnt(0) expcnt(0) lgkmcnt(0)
	ds_read_b32 v2, v0
	s_add_i32 s10, 0, 0x22024
	v_mov_b32_e32 v0, s10
	ds_read_b32 v0, v0
	s_waitcnt lgkmcnt(1)
	v_cmp_ne_u32_e32 vcc, 0, v2
	s_cbranch_vccnz .LBB0_131
	s_add_u32 s10, s30, 0x40200
	s_addc_u32 s11, s31, 0
	s_add_u32 s12, s30, 0x40400
	s_addc_u32 s13, s31, 0
	s_add_u32 s14, s30, 0x40500
	s_addc_u32 s15, s31, 0
	s_add_u32 s16, s30, 0x40600
	s_addc_u32 s17, s31, 0
	s_add_u32 s18, s30, 0x40700
	s_addc_u32 s19, s31, 0
	s_add_u32 s20, s30, 0x40800
	s_addc_u32 s21, s31, 0
	s_add_u32 s22, s30, 0x40900
	s_addc_u32 s23, s31, 0
	s_add_u32 s24, s30, 0x40a00
	s_addc_u32 s25, s31, 0
	s_add_u32 s36, s30, 0x40b00
	s_addc_u32 s37, s31, 0
	s_add_u32 s38, s30, 0x40c00
	s_addc_u32 s39, s31, 0
	s_add_u32 s40, s30, 0x40d00
	s_addc_u32 s41, s31, 0
	s_add_u32 s42, s30, 0x40e00
	s_addc_u32 s43, s31, 0
	s_add_u32 s44, s30, 0x40f00
	s_addc_u32 s45, s31, 0
	s_add_u32 s46, s30, 0x41000
	s_addc_u32 s47, s31, 0
	s_add_u32 s48, s30, 0x41100
	s_addc_u32 s49, s31, 0
	s_add_u32 s50, s30, 0x41200
	s_addc_u32 s51, s31, 0
	s_mul_i32 s61, s29, s90
	s_add_u32 s52, s30, 0x41300
	s_mul_i32 s61, s61, s28
	s_addc_u32 s53, s31, 0
	s_mov_b32 s62, 1
	v_mov_b32_e32 v16, 0
	s_branch .LBB0_119

.LBB0_226:
	s_mov_b32 s101, 0
	s_cmp_gt_i32 s89, 2
	s_cselect_b64 s[6:7], -1, 0
	s_and_b64 s[8:9], s[36:37], s[6:7]
	s_andn2_b64 vcc, exec, s[8:9]
	s_cbranch_vccnz .LBB0_280
	s_waitcnt vmcnt(0)
	s_waitcnt vmcnt(0) lgkmcnt(0)
	s_barrier
	v_readfirstlane_b32 s98, v208
	s_cmp_eq_u32 s98, 64
	s_cbranch_scc0 .Lseam_inv_skip_1
	buffer_inv sc1
	s_waitcnt vmcnt(0)

.LBB0_517:
	s_cmp_gt_i32 s89, 3
	s_cselect_b64 s[4:5], -1, 0
	s_and_b64 s[6:7], s[20:21], s[4:5]
	s_andn2_b64 vcc, exec, s[6:7]
	s_cbranch_vccnz .LBB0_571
	s_waitcnt vmcnt(0)
	s_waitcnt vmcnt(0) lgkmcnt(0)
	s_barrier
	v_readfirstlane_b32 s98, v208
	s_cmp_eq_u32 s98, 64
	s_cbranch_scc0 .Lseam_inv_skip_2
	buffer_inv sc1
	s_waitcnt vmcnt(0)
.Lseam_inv_skip_2:
	s_and_saveexec_b64 s[6:7], s[26:27]
	s_cbranch_execz .LBB0_570
	s_add_i32 s8, 0, 0x22020
	v_mov_b32_e32 v0, s8
	s_waitcnt vmcnt(0) expcnt(0) lgkmcnt(0)
	ds_read_b32 v2, v0
	s_add_i32 s8, 0, 0x22024
	v_mov_b32_e32 v0, s8
	ds_read_b32 v0, v0
	s_waitcnt lgkmcnt(1)
	v_cmp_ne_u32_e32 vcc, 0, v2
	s_cbranch_vccnz .LBB0_534
	s_add_u32 s8, s30, 0x40200
	s_addc_u32 s9, s31, 0
	s_add_u32 s10, s30, 0x40400
	s_addc_u32 s11, s31, 0
	s_add_u32 s12, s30, 0x40500
	s_addc_u32 s13, s31, 0
	s_add_u32 s14, s30, 0x40600
	s_addc_u32 s15, s31, 0
	s_add_u32 s16, s30, 0x40700
	s_addc_u32 s17, s31, 0
	s_add_u32 s18, s30, 0x40800
	s_addc_u32 s19, s31, 0
	s_add_u32 s20, s30, 0x40900
	s_addc_u32 s21, s31, 0
	s_add_u32 s22, s30, 0x40a00
	s_addc_u32 s23, s31, 0
	s_add_u32 s24, s30, 0x40b00
	s_addc_u32 s25, s31, 0
	s_add_u32 s36, s30, 0x40c00
	s_addc_u32 s37, s31, 0
	s_add_u32 s38, s30, 0x40d00
	s_addc_u32 s39, s31, 0
	s_add_u32 s40, s30, 0x40e00
	s_addc_u32 s41, s31, 0
	s_add_u32 s42, s30, 0x40f00
	s_addc_u32 s43, s31, 0
	s_add_u32 s44, s30, 0x41000
	s_addc_u32 s45, s31, 0
	s_add_u32 s46, s30, 0x41100
	s_addc_u32 s47, s31, 0
	s_add_u32 s48, s30, 0x41200
	s_addc_u32 s49, s31, 0
	s_mul_i32 s58, s29, s90
	s_add_u32 s50, s30, 0x41300
	s_mul_i32 s58, s58, s28
	s_addc_u32 s51, s31, 0
	s_mov_b32 s59, 1
	v_mov_b32_e32 v16, 0
	s_branch .LBB0_522

.LBB0_630:
	s_cmp_gt_i32 s89, 4
	s_waitcnt lgkmcnt(0)
	s_cselect_b64 s[4:5], -1, 0
	s_and_b64 s[6:7], s[10:11], s[4:5]
	s_andn2_b64 vcc, exec, s[6:7]
	s_cbranch_vccnz .LBB0_684
	s_waitcnt vmcnt(0)
	s_waitcnt vmcnt(0)
	s_barrier
	v_readfirstlane_b32 s98, v208
	s_cmp_eq_u32 s98, 64
	s_cbranch_scc0 .Lseam_inv_skip_3
	buffer_inv sc1
	s_waitcnt vmcnt(0)

.LBB0_709:
	s_cmp_gt_i32 s89, 5
	s_cselect_b64 s[4:5], -1, 0
	s_and_b64 s[6:7], s[6:7], s[4:5]
	s_andn2_b64 vcc, exec, s[6:7]
	s_cbranch_vccnz .LBB0_763
	s_waitcnt vmcnt(0)
	s_waitcnt vmcnt(0)
	s_barrier
	v_readfirstlane_b32 s98, v208
	s_cmp_eq_u32 s98, 64
	s_cbranch_scc0 .Lseam_inv_skip_4
	buffer_inv sc1
	s_waitcnt vmcnt(0)
.Lseam_inv_skip_4:
	s_and_saveexec_b64 s[6:7], s[26:27]
	s_cbranch_execz .LBB0_762
	s_cmp_eq_u32 s100, 0
	s_cbranch_scc1 .Lgrp_full_4
	s_and_b32 s98, s2, 63
	s_lshl_b32 s98, s98, 2
	v_mov_b32_e32 v0, s98
	v_mov_b32_e32 v1, 1
	global_atomic_add v0, v1, s[34:35]
	s_mov_b32 s99, 0

.LBB0_830:
	s_cmp_gt_i32 s89, 6
	s_waitcnt lgkmcnt(0)
	s_cselect_b64 s[4:5], -1, 0
	s_and_b64 s[6:7], s[10:11], s[4:5]
	s_andn2_b64 vcc, exec, s[6:7]
	s_cbranch_vccnz .LBB0_884
	s_waitcnt vmcnt(0)
	s_waitcnt vmcnt(0)
	s_barrier
	v_readfirstlane_b32 s98, v208
	s_cmp_eq_u32 s98, 64
	s_cbranch_scc0 .Lseam_inv_skip_5
	buffer_inv sc1
	s_waitcnt vmcnt(0)

.LBB0_909:
	s_cmp_gt_i32 s89, 7
	s_cselect_b64 s[4:5], -1, 0
	s_and_b64 s[6:7], s[6:7], s[4:5]
	s_andn2_b64 vcc, exec, s[6:7]
	s_cbranch_vccnz .LBB0_963
	s_waitcnt vmcnt(0)
	s_waitcnt vmcnt(0)
	s_barrier
	v_readfirstlane_b32 s98, v208
	s_cmp_eq_u32 s98, 64
	s_cbranch_scc0 .Lseam_inv_skip_6
	buffer_inv sc1
	s_waitcnt vmcnt(0)

.LBB0_980:
	s_cmp_gt_i32 s89, 8
	s_cselect_b64 s[6:7], -1, 0
	s_and_b64 s[8:9], s[10:11], s[6:7]
	s_andn2_b64 vcc, exec, s[8:9]
	s_cbranch_vccnz .LBB0_1034
	s_waitcnt vmcnt(0)
	s_waitcnt vmcnt(0)
	s_barrier
	v_readfirstlane_b32 s98, v208
	s_cmp_eq_u32 s98, 64
	s_cbranch_scc0 .Lseam_inv_skip_7
	buffer_inv sc1
	s_waitcnt vmcnt(0)
.Lseam_inv_skip_7:
	s_and_saveexec_b64 s[8:9], s[26:27]
	s_cbranch_execz .LBB0_1033
	s_add_i32 s10, 0, 0x22020
	v_mov_b32_e32 v0, s10
	s_waitcnt vmcnt(0) expcnt(0) lgkmcnt(0)
	ds_read_b32 v2, v0
	s_add_i32 s10, 0, 0x22024
	v_mov_b32_e32 v0, s10
	ds_read_b32 v0, v0
	s_waitcnt lgkmcnt(1)
	v_cmp_ne_u32_e32 vcc, 0, v2
	s_cbranch_vccnz .LBB0_997
	s_add_u32 s10, s30, 0x40200
	s_addc_u32 s11, s31, 0
	s_add_u32 s12, s30, 0x40400
	s_addc_u32 s13, s31, 0
	s_add_u32 s14, s30, 0x40500
	s_addc_u32 s15, s31, 0
	s_add_u32 s16, s30, 0x40600
	s_addc_u32 s17, s31, 0
	s_add_u32 s18, s30, 0x40700
	s_addc_u32 s19, s31, 0
	s_add_u32 s20, s30, 0x40800
	s_addc_u32 s21, s31, 0
	s_add_u32 s22, s30, 0x40900
	s_addc_u32 s23, s31, 0
	s_add_u32 s24, s30, 0x40a00
	s_addc_u32 s25, s31, 0
	s_add_u32 s36, s30, 0x40b00
	s_addc_u32 s37, s31, 0
	s_add_u32 s38, s30, 0x40c00
	s_addc_u32 s39, s31, 0
	s_add_u32 s40, s30, 0x40d00
	s_addc_u32 s41, s31, 0
	s_add_u32 s42, s30, 0x40e00
	s_addc_u32 s43, s31, 0
	s_add_u32 s44, s30, 0x40f00
	s_addc_u32 s45, s31, 0
	s_add_u32 s46, s30, 0x41000
	s_addc_u32 s47, s31, 0
	s_add_u32 s48, s30, 0x41100
	s_addc_u32 s49, s31, 0
	s_add_u32 s50, s30, 0x41200
	s_addc_u32 s51, s31, 0
	s_mul_i32 s60, s29, s90
	s_add_u32 s52, s30, 0x41300
	s_mul_i32 s60, s60, s28
	s_addc_u32 s53, s31, 0
	s_mov_b32 s61, 1
	v_mov_b32_e32 v16, 0
	s_branch .LBB0_985

.LBB0_1048:
	s_cmp_gt_u32 s89, 9
	s_cselect_b64 s[10:11], -1, 0
	s_and_b64 s[8:9], s[8:9], s[10:11]
	s_mov_b64 s[6:7], 0
	s_andn2_b64 vcc, exec, s[8:9]
	s_mov_b64 s[8:9], 0
	s_cbranch_vccnz .LBB0_1102
	s_waitcnt vmcnt(0)
	s_waitcnt vmcnt(0)
	s_barrier
	v_readfirstlane_b32 s98, v208
	s_cmp_eq_u32 s98, 64
	s_cbranch_scc0 .Lseam_inv_skip_8
	buffer_inv sc1
	s_waitcnt vmcnt(0)

.LBB0_1153:
	s_cmp_gt_i32 s89, 10
	s_cselect_b64 s[4:5], -1, 0
	s_and_b64 s[6:7], s[8:9], s[4:5]
	s_andn2_b64 vcc, exec, s[6:7]
	s_cbranch_vccnz .LBB0_1207
	s_waitcnt vmcnt(0)
	s_waitcnt vmcnt(0)
	s_barrier
	v_readfirstlane_b32 s98, v208
	s_cmp_eq_u32 s98, 64
	s_cbranch_scc0 .Lseam_inv_skip_9
	buffer_inv sc1
	s_waitcnt vmcnt(0)

.LBB0_1250:
	s_cmp_gt_i32 s89, 11
	s_waitcnt lgkmcnt(0)
	s_cselect_b64 s[4:5], -1, 0
	s_and_b64 s[6:7], s[8:9], s[4:5]
	s_andn2_b64 vcc, exec, s[6:7]
	s_cbranch_vccnz .LBB0_1304
	s_waitcnt vmcnt(0)
	s_waitcnt vmcnt(0)
	s_barrier
	v_readfirstlane_b32 s98, v208
	s_cmp_eq_u32 s98, 64
	s_cbranch_scc0 .Lseam_inv_skip_10
	buffer_inv sc1
	s_waitcnt vmcnt(0)

.LBB0_1329:
	s_cmp_gt_i32 s89, 12
	s_cselect_b64 s[4:5], -1, 0
	s_and_b64 s[6:7], s[6:7], s[4:5]
	s_andn2_b64 vcc, exec, s[6:7]
	s_cbranch_vccnz .LBB0_1383
	s_waitcnt vmcnt(0)
	s_waitcnt vmcnt(0)
	s_barrier
	v_readfirstlane_b32 s98, v208
	s_cmp_eq_u32 s98, 64
	s_cbranch_scc0 .Lseam_inv_skip_11
	buffer_inv sc1
	s_waitcnt vmcnt(0)
